# the one cooperative-groups grid sync after the prologue replaced by the kernel's own XCD-hierarchical barrier (block 0 publishes a READY word after zeroing the barrier words; SEAM(1)'s barrier code en
# speedup vs baseline: 1.0440x; 1.0159x over previous
_Z8fwd_mega4Args:
	s_mov_b32 s99, 0
	s_load_dword s3, s[0:1], 0x108
	s_load_dwordx2 s[30:31], s[0:1], 0x100
	s_load_dwordx8 s[36:43], s[0:1], 0xe0
	s_load_dwordx8 s[8:15], s[0:1], 0xc0
	s_add_u32 s6, s0, 0x100
	v_and_b32_e32 v144, 0x3ff, v0
	s_addc_u32 s7, s1, 0
	s_waitcnt lgkmcnt(0)
	v_writelane_b32 v240, s3, 0
	v_writelane_b32 v240, s8, 1
	v_readfirstlane_b32 s33, v144
	s_nop 0
	v_writelane_b32 v240, s9, 2
	v_writelane_b32 v240, s10, 3
	v_writelane_b32 v240, s11, 4
	v_writelane_b32 v240, s12, 5
	v_writelane_b32 v240, s13, 6
	v_writelane_b32 v240, s14, 7
	v_writelane_b32 v240, s15, 8
	v_cmp_eq_u32_e64 s[8:9], 0, v144
	s_mov_b64 s[4:5], exec
	s_nop 0
	v_writelane_b32 v240, s8, 9
	s_nop 1
	v_writelane_b32 v240, s9, 10
	s_and_b64 s[8:9], s[4:5], s[8:9]
	s_mov_b64 exec, s[8:9]
	s_cbranch_execz .LBB0_2
	s_add_i32 s3, 0, 0x23fc0
	v_mov_b32_e32 v1, 0
	v_mov_b32_e32 v2, s3
	s_add_i32 s3, 0, 0x23fc4
	ds_write_b32 v2, v1
	v_mov_b32_e32 v2, s3
	ds_write_b32 v2, v1

.LBB0_9:
	s_or_b64 exec, exec, s[10:11]
	s_waitcnt vmcnt(0)
	s_load_dwordx8 s[48:55], s[0:1], 0xe0
.LBB0_10:
	s_lshr_b32 s57, s33, 6
	s_lshl_b32 s3, s2, 3
	s_add_i32 s34, s57, s3
	s_lshl_b32 s80, s30, 3
	s_waitcnt lgkmcnt(0)
	s_add_u32 s82, s52, 0x8000000
	s_addc_u32 s83, s53, 0
	s_load_dwordx16 s[36:51], s[0:1], 0x40
	s_cmp_lt_i32 s54, 1
	s_cselect_b64 s[4:5], -1, 0
	s_cmp_gt_i32 s55, 0
	s_cselect_b64 s[8:9], -1, 0
	s_and_b64 s[4:5], s[4:5], s[8:9]
	v_and_b32_e32 v146, 63, v144
	s_andn2_b64 vcc, exec, s[4:5]
	s_waitcnt lgkmcnt(0)
	s_barrier
	s_cmp_lg_u32 s2, 0
	s_cbranch_scc1 .Lflag_set_done
	v_readlane_b32 s4, v240, 9
	v_readlane_b32 s5, v240, 10
	s_mov_b64 s[8:9], exec
	s_and_b64 exec, exec, s[4:5]
	s_cbranch_execz .Lflag_set_skip
	buffer_wbl2 sc1
	s_waitcnt vmcnt(0)
	v_mov_b32_e32 v1, 0x5eed0ba5
	v_mov_b32_e32 v2, 0x3800
	global_store_dword v2, v1, s[88:89] sc0 sc1
	s_waitcnt vmcnt(0)
.Lflag_set_skip:
	s_mov_b64 exec, s[8:9]
.Lflag_set_done:
	s_cbranch_vccnz .LBB0_57
	s_cmpk_gt_i32 s34, 0x2bff
	s_cbranch_scc1 .LBB0_30
	s_load_dwordx8 s[60:67], s[0:1], 0xe0
	s_mul_i32 s3, s57, 0x2100
	v_and_b32_e32 v2, 7, v144
	s_add_i32 s3, s3, 0
	v_lshrrev_b32_e32 v1, 3, v146
	v_lshlrev_b32_e32 v6, 4, v2
	v_mov_b32_e32 v7, 0
	v_lshlrev_b32_e32 v12, 2, v2
	v_add_u32_e32 v4, s3, v6
	v_mul_u32_u24_e32 v5, 0x84, v1
	v_mul_u32_u24_e32 v10, 0x420, v2
	s_waitcnt lgkmcnt(0)
	v_lshl_add_u64 v[2:3], s[64:65], 0, v[6:7]
	s_mov_b64 s[4:5], 0x100000
	v_lshl_add_u64 v[8:9], v[2:3], 0, s[4:5]
	v_lshlrev_b32_e32 v2, 2, v1
	s_movk_i32 s4, 0xfe00
	v_add_u32_e32 v21, v4, v5
	v_or_b32_e32 v13, 8, v1
	v_or_b32_e32 v14, 16, v1
	v_or_b32_e32 v15, 24, v1
	v_or_b32_e32 v16, 32, v1
	v_or_b32_e32 v17, 40, v1
	v_or_b32_e32 v18, 48, v1
	v_or_b32_e32 v19, 56, v1
	v_add3_u32 v20, s3, v10, v2
	s_lshl_b32 s3, s34, 5
	s_lshl_b32 s28, s80, 5
	s_lshl_b32 s29, s34, 4
	s_lshl_b32 s35, s80, 4
	s_mov_b32 s5, -1
	s_movk_i32 s52, 0x5800
	v_add_u32_e32 v22, 0x420, v21
	v_add_u32_e32 v23, 0x428, v21
	v_add_u32_e32 v24, 0x840, v21
	v_add_u32_e32 v25, 0x848, v21
	s_movk_i32 s53, 0x7fff
	s_mov_b32 s54, 0xffff0000
	v_add_u32_e32 v26, 0xc60, v21
	v_add_u32_e32 v27, 0xc68, v21
	v_add_u32_e32 v28, 0x1080, v21
	v_add_u32_e32 v29, 0x1088, v21
	s_mov_b32 s55, s34
	s_branch .LBB0_14

.LBB0_57:
	v_lshrrev_b32_e32 v1, 20, v0
	v_lshrrev_b32_e32 v0, 10, v0
	v_or_b32_e32 v0, v0, v1
	s_movk_i32 s3, 0x3ff
	v_and_or_b32 v0, v0, s3, v144
	v_cmp_eq_u32_e32 vcc, 0, v0
	s_waitcnt lgkmcnt(0)
	s_barrier
	s_and_saveexec_b64 s[4:5], vcc
	s_load_dwordx8 s[48:55], s[0:1], 0xe0
	s_cbranch_execz .LBB0_67
	s_waitcnt lgkmcnt(0)
	v_mov_b32_e32 v2, 0x3800
	s_mov_b32 s3, 0
.Lflag_wait:
	global_load_dword v1, v2, s[88:89] sc1
	s_waitcnt vmcnt(0)
	v_cmp_ne_u32_e32 vcc, 0x5eed0ba5, v1
	s_cbranch_vccz .Lflag_ok
	s_sleep 1
	s_add_u32 s3, s3, 1
	s_cmp_lt_u32 s3, 0x4000
	s_cbranch_scc1 .Lflag_wait
.Lflag_ok:
.LBB0_67:
	s_or_b64 exec, exec, s[4:5]
	s_load_dwordx16 s[60:75], s[0:1], 0x80
	s_barrier
	s_waitcnt lgkmcnt(0)
	s_getreg_b32 s0, hwreg(HW_REG_XCC_ID, 0, 4)
	s_and_b32 s56, s0, 15
	v_writelane_b32 v240, s60, 19
	s_nop 1
	v_writelane_b32 v240, s61, 20
	v_writelane_b32 v240, s62, 21
	v_writelane_b32 v240, s63, 22
	v_writelane_b32 v240, s64, 23
	v_writelane_b32 v240, s65, 24
	v_writelane_b32 v240, s66, 25
	v_writelane_b32 v240, s67, 26
	v_writelane_b32 v240, s68, 27
	v_writelane_b32 v240, s69, 28
	v_writelane_b32 v240, s70, 29
	v_writelane_b32 v240, s71, 30
	v_writelane_b32 v240, s72, 31
	v_writelane_b32 v240, s73, 32
	v_writelane_b32 v240, s74, 33
	v_writelane_b32 v240, s75, 34
	s_mov_b64 s[0:1], exec
	v_readlane_b32 s4, v240, 9
	v_readlane_b32 s5, v240, 10
	s_and_b64 s[4:5], s[0:1], s[4:5]
	s_mov_b64 exec, s[4:5]
	s_cbranch_execz .LBB0_70
	s_mov_b64 s[4:5], exec
	v_mbcnt_lo_u32_b32 v0, s4, 0
	v_mbcnt_hi_u32_b32 v0, s5, v0
	v_cmp_eq_u32_e32 vcc, 0, v0
	s_and_b64 s[6:7], exec, vcc
	s_mov_b64 exec, s[6:7]
	s_cbranch_execz .LBB0_70
	s_lshl_b32 s3, s56, 8
	s_bcnt1_i32_b64 s4, s[4:5]
	v_mov_b32_e32 v0, s3
	v_mov_b32_e32 v1, s4
	global_atomic_add v0, v1, s[88:89] offset:1024
.LBB0_70:
	s_or_b64 exec, exec, s[0:1]
	v_writelane_b32 v240, s88, 35
	v_writelane_b32 v240, s89, 36
	v_writelane_b32 v241, s10, 0
	v_writelane_b32 v241, s11, 1
	v_writelane_b32 v241, s16, 2
	v_writelane_b32 v241, s17, 3
	v_writelane_b32 v241, s18, 4
	v_writelane_b32 v241, s19, 5
	v_writelane_b32 v241, s20, 6
	v_writelane_b32 v241, s21, 7
	v_writelane_b32 v241, s24, 8
	v_writelane_b32 v241, s25, 9
	v_writelane_b32 v241, s50, 10
	v_writelane_b32 v241, s51, 11
	v_writelane_b32 v241, s52, 12
	v_writelane_b32 v241, s53, 13
	v_writelane_b32 v241, s54, 14
	v_writelane_b32 v241, s55, 15
	v_writelane_b32 v241, s85, 16
	v_writelane_b32 v241, s86, 17
	v_writelane_b32 v241, s88, 18
	v_writelane_b32 v241, s89, 19
	v_mov_b32_e32 v242, v3
	v_mov_b32_e32 v243, v4
	v_mov_b32_e32 v244, v5
	v_mov_b32_e32 v245, v6
	v_mov_b32_e32 v246, v7
	s_mov_b32 s99, 1
	s_branch .LBB0_132
.Lcgx_back:
	s_waitcnt lgkmcnt(0)
	s_barrier
	s_mov_b32 s99, 0
	v_readlane_b32 s10, v241, 0
	v_readlane_b32 s11, v241, 1
	v_readlane_b32 s16, v241, 2
	v_readlane_b32 s17, v241, 3
	v_readlane_b32 s18, v241, 4
	v_readlane_b32 s19, v241, 5
	v_readlane_b32 s20, v241, 6
	v_readlane_b32 s21, v241, 7
	v_readlane_b32 s24, v241, 8
	v_readlane_b32 s25, v241, 9
	v_readlane_b32 s50, v241, 10
	v_readlane_b32 s51, v241, 11
	v_readlane_b32 s52, v241, 12
	v_readlane_b32 s53, v241, 13
	v_readlane_b32 s54, v241, 14
	v_readlane_b32 s55, v241, 15
	v_readlane_b32 s85, v241, 16
	v_readlane_b32 s86, v241, 17
	v_readlane_b32 s88, v241, 18
	v_readlane_b32 s89, v241, 19
	v_mov_b32_e32 v3, v242
	v_mov_b32_e32 v4, v243
	v_mov_b32_e32 v5, v244
	v_mov_b32_e32 v6, v245
	v_mov_b32_e32 v7, v246
	s_nop 4
	s_add_u32 s44, s52, 0xe000000
	s_addc_u32 s45, s53, 0
	s_cmp_lt_i32 s54, 2
	s_cselect_b64 s[0:1], -1, 0
	s_cmp_gt_i32 s55, 1
	s_cselect_b64 s[4:5], -1, 0
	s_and_b64 s[0:1], s[0:1], s[4:5]
	s_andn2_b64 vcc, exec, s[0:1]
	v_writelane_b32 v240, s88, 35
	s_nop 1
	v_writelane_b32 v240, s89, 36
	s_cbranch_vccnz .LBB0_132
	s_cmpk_gt_i32 s2, 0x57f
	v_readfirstlane_b32 s1, v144
	s_cbranch_scc1 .LBB0_87
	v_lshrrev_b32_e32 v0, 5, v144
	v_lshrrev_b32_e32 v2, 1, v144
	v_and_b32_e32 v0, 4, v0
	v_bfe_u32 v1, v144, 2, 2
	v_and_b32_e32 v11, 24, v2
	v_or3_b32 v0, v0, v1, v11
	v_lshlrev_b32_e32 v1, 4, v144
	v_add_u32_e32 v8, 0x2000, v1
	v_lshrrev_b32_e32 v2, 7, v8
	s_movk_i32 s0, 0xe0
	v_and_b32_e32 v4, 32, v144
	v_and_or_b32 v3, v2, s0, v0
	v_bitop3_b32 v9, v1, v4, 48 bitop3:0x6c
	v_and_b32_e32 v10, 64, v144
	v_bfe_u32 v12, v144, 2, 4
	s_movk_i32 s0, 0xf0
	v_or_b32_e32 v1, v9, v10
	v_and_or_b32 v2, v2, s0, v12
	s_add_u32 s3, s52, 0x100000
	v_lshl_or_b32 v130, v2, 12, v1
	v_lshrrev_b32_e32 v2, 3, v144
	s_movk_i32 s0, 0x60
	s_addc_u32 s28, s53, 0
	v_and_or_b32 v0, v2, s0, v0
	s_movk_i32 s0, 0x70
	s_ashr_i32 s35, s2, 31
	v_lshl_or_b32 v132, v0, 12, v1
	v_and_or_b32 v0, v2, s0, v12
	s_lshr_b32 s0, s35, 29
	s_add_i32 s0, s2, s0
	s_lshr_b32 s6, s1, 6
	s_ashr_i32 s4, s0, 3
	s_and_b32 s0, s0, -8
	s_lshr_b32 s8, s1, 8
	s_lshl_b32 s29, s6, 10
	s_sub_i32 s0, s2, s0
	s_cmp_lt_i32 s0, 0
	s_movk_i32 s48, 0xb1
	s_cselect_b32 s5, s48, 0xb0
	s_mul_i32 s0, s0, s5
	s_add_i32 s0, s0, s4
	s_mul_hi_i32 s4, s0, 0x2e8ba2e9
	s_lshr_b32 s5, s4, 31
	s_ashr_i32 s4, s4, 6
	s_add_i32 s4, s4, s5
	s_lshl_b32 s5, s4, 3
	s_mulk_i32 s4, 0x160
	s_sub_i32 s4, s0, s4
	s_sext_i32_i16 s0, s4
	s_bfe_u32 s0, s0, 0x3001c
	s_add_i32 s7, s4, s0
	s_sext_i32_i16 s0, s7
	s_and_b32 s7, s7, 0xfff8
	s_sub_i32 s4, s4, s7
	s_sext_i32_i16 s4, s4
	s_lshr_b32 s0, s0, 3
	s_add_i32 s86, s5, s4
	s_ashr_i32 s87, s86, 31
	s_bfe_i64 s[10:11], s[0:1], 0x100000
	s_lshl_b64 s[4:5], s[86:87], 20
	s_lshl_b64 s[10:11], s[10:11], 20
	s_add_u32 s90, s3, s10
	s_addc_u32 s91, s28, s11
	s_add_i32 s49, s29, 0
	s_add_i32 m0, s49, 0x10000
	v_lshl_or_b32 v128, v3, 12, v1
	global_load_lds_dwordx4 v132, s[90:91]
	s_add_i32 m0, s49, 0x12000
	s_add_u32 s10, s90, 0x80000
	global_load_lds_dwordx4 v128, s[90:91]
	s_addc_u32 s11, s91, 0
	s_add_i32 m0, s49, 0x14000
	v_lshl_or_b32 v134, v0, 12, v1
	global_load_lds_dwordx4 v132, s[10:11]
	s_add_i32 m0, s49, 0x16000
	s_add_u32 s88, s82, s4
	s_addc_u32 s89, s83, s5
	s_add_i32 s50, s49, 0x2000
	global_load_lds_dwordx4 v128, s[10:11]
	s_mov_b32 m0, s49
	s_add_u32 s4, s88, 0x80000
	global_load_lds_dwordx4 v134, s[88:89]
	s_mov_b32 m0, s50
	s_addc_u32 s5, s89, 0
	s_add_i32 s51, s49, 0x4000
	global_load_lds_dwordx4 v130, s[88:89]
	s_mov_b32 m0, s51
	s_add_i32 s52, s49, 0x6000
	global_load_lds_dwordx4 v134, s[4:5]
	s_mov_b32 m0, s52
	v_mov_b32_e32 v133, 0
	global_load_lds_dwordx4 v130, s[4:5]
	v_mov_b32_e32 v129, v133
	v_mov_b32_e32 v135, v133
	v_mov_b32_e32 v131, v133
	s_cmp_eq_u32 s8, 1
	s_mov_b32 s53, 0
	v_lshl_add_u64 v[6:7], s[90:91], 0, v[132:133]
	v_lshl_add_u64 v[4:5], s[90:91], 0, v[128:129]
	v_lshl_add_u64 v[0:1], s[88:89], 0, v[134:135]
	s_cselect_b64 s[4:5], -1, 0
	s_cmp_lg_u32 s8, 1
	v_lshl_add_u64 v[2:3], s[88:89], 0, v[130:131]
	s_cbranch_scc1 .LBB0_74
	s_barrier

.LBB0_184:
	s_or_b64 exec, exec, s[0:1]
	s_cmp_eq_u32 s99, 1
	s_cbranch_scc1 .Lcgx_back
	s_add_u32 s24, s52, 0xa000000
	s_addc_u32 s25, s53, 0
	s_cmp_lt_i32 s54, 3
	s_cselect_b64 s[0:1], -1, 0
	s_cmp_gt_i32 s55, 2
	s_cselect_b64 s[4:5], -1, 0
	s_and_b64 s[0:1], s[0:1], s[4:5]
	s_andn2_b64 vcc, exec, s[0:1]
	s_waitcnt lgkmcnt(0)
	s_barrier
	s_cbranch_vccnz .LBB0_271
	s_cmpk_lt_i32 s2, 0x100
	s_cselect_b64 s[0:1], -1, 0
	s_cmpk_gt_i32 s2, 0xff
	v_readfirstlane_b32 s6, v144
	s_cbranch_scc1 .LBB0_191
	s_ashr_i32 s3, s2, 31
	s_lshr_b32 s3, s3, 29
	s_add_i32 s3, s2, s3
	s_and_b32 s4, s3, -8
	s_sub_i32 s7, s2, s4
	s_cmp_gt_i32 s7, -1
	s_cbranch_scc0 .LBB0_188
	s_lshl_b32 s8, s7, 5
	s_cbranch_execz .LBB0_189
	s_branch .LBB0_190

.LBB0_1517:
	s_cmp_lg_u32 s2, 0
	s_cbranch_scc1 .Lflag_clr_done0
	v_readlane_b32 s4, v240, 9
	v_readlane_b32 s5, v240, 10
	v_readlane_b32 s6, v240, 35
	v_readlane_b32 s7, v240, 36
	s_and_b64 exec, exec, s[4:5]
	s_cbranch_execz .Lflag_clr_done0
	v_mov_b32_e32 v1, 0
	v_mov_b32_e32 v2, 0x3800
	s_nop 4
	global_store_dword v2, v1, s[6:7] sc0 sc1

.LBB0_1612:
	s_or_b64 exec, exec, s[2:3]
	v_lshlrev_b64 v[130:131], 2, v[130:131]
	v_lshl_add_u64 v[8:9], s[48:49], 0, v[130:131]
	v_lshlrev_b64 v[164:165], 11, v[156:157]
	v_lshlrev_b64 v[156:157], 11, v[160:161]
	s_waitcnt lgkmcnt(0)
	s_barrier
	global_load_dwordx4 v[4:7], v[8:9], off offset:16
	global_load_dwordx4 v[12:15], v[8:9], off
	global_load_dwordx4 v[0:3], v[8:9], off offset:528
	s_nop 0
	global_load_dwordx4 v[8:11], v[8:9], off offset:512
	s_nop 0
	global_load_dword v161, v[112:113], off sc1
	v_mov_b32_e32 v160, 0x358637bd
	s_mov_b32 s2, 0x800000
	v_lshlrev_b64 v[172:173], 11, v[134:135]
	v_lshlrev_b64 v[134:135], 11, v[162:163]
	v_lshlrev_b64 v[170:171], 11, v[132:133]
	v_lshl_add_u64 v[132:133], v[132:133], 2, s[0:1]
	v_lshlrev_b64 v[168:169], 11, v[136:137]
	v_lshlrev_b64 v[166:167], 11, v[138:139]
	v_lshlrev_b64 v[158:159], 11, v[158:159]
	s_waitcnt vmcnt(0)
	v_fmamk_f32 v161, v161, 0x3a000000, v160
	v_mul_f32_e32 v162, 0x4b800000, v161
	v_cmp_gt_f32_e32 vcc, s2, v161
	s_nop 1
	v_cndmask_b32_e32 v161, v161, v162, vcc
	v_rsq_f32_e32 v161, v161
	v_lshl_add_u64 v[162:163], v[172:173], 2, s[50:51]
	v_lshl_add_u64 v[162:163], v[162:163], 0, v[130:131]
	v_mul_f32_e32 v172, 0x45800000, v161
	v_cndmask_b32_e32 v172, v161, v172, vcc
	v_pk_mul_f32 v[124:125], v[124:125], v[172:173] op_sel_hi:[1,0]
	v_pk_mul_f32 v[126:127], v[126:127], v[172:173] op_sel_hi:[1,0]
	v_pk_mul_f32 v[174:175], v[120:121], v[172:173] op_sel_hi:[1,0]
	v_pk_mul_f32 v[120:121], v[122:123], v[172:173] op_sel_hi:[1,0]
	v_pk_mul_f32 v[122:123], v[116:117], v[172:173] op_sel_hi:[1,0]
	v_pk_mul_f32 v[176:177], v[118:119], v[172:173] op_sel_hi:[1,0]
	v_pk_mul_f32 v[178:179], v[128:129], v[172:173] op_sel_hi:[1,0]
	v_pk_mul_f32 v[128:129], v[114:115], v[172:173] op_sel_hi:[1,0]
	v_pk_mul_f32 v[116:117], v[14:15], v[126:127]
	v_pk_mul_f32 v[114:115], v[12:13], v[124:125]
	v_pk_mul_f32 v[120:121], v[6:7], v[120:121]
	v_pk_mul_f32 v[118:119], v[4:5], v[174:175]
	v_pk_mul_f32 v[124:125], v[10:11], v[176:177]
	v_pk_mul_f32 v[122:123], v[8:9], v[122:123]
	v_pk_mul_f32 v[128:129], v[2:3], v[128:129]
	v_pk_mul_f32 v[126:127], v[0:1], v[178:179]
	global_store_dwordx4 v[162:163], v[114:117], off
	global_store_dwordx4 v[162:163], v[118:121], off offset:16
	global_store_dwordx4 v[162:163], v[122:125], off offset:512
	global_store_dwordx4 v[162:163], v[126:129], off offset:528
	global_load_dword v114, v[132:133], off sc1
	v_lshl_add_u64 v[116:117], v[136:137], 2, s[0:1]
	s_waitcnt vmcnt(0)
	v_fmamk_f32 v114, v114, 0x3a000000, v160
	v_mul_f32_e32 v115, 0x4b800000, v114
	v_cmp_gt_f32_e32 vcc, s2, v114
	s_nop 1
	v_cndmask_b32_e32 v114, v114, v115, vcc
	v_rsq_f32_e32 v118, v114
	v_lshl_add_u64 v[114:115], v[170:171], 2, s[50:51]
	v_lshl_add_u64 v[114:115], v[114:115], 0, v[130:131]
	v_mul_f32_e32 v119, 0x45800000, v118
	v_cndmask_b32_e32 v118, v118, v119, vcc
	v_pk_mul_f32 v[108:109], v[108:109], v[118:119] op_sel_hi:[1,0]
	v_pk_mul_f32 v[110:111], v[110:111], v[118:119] op_sel_hi:[1,0]
	v_pk_mul_f32 v[104:105], v[104:105], v[118:119] op_sel_hi:[1,0]
	v_pk_mul_f32 v[106:107], v[106:107], v[118:119] op_sel_hi:[1,0]
	v_pk_mul_f32 v[120:121], v[100:101], v[118:119] op_sel_hi:[1,0]
	v_pk_mul_f32 v[122:123], v[102:103], v[118:119] op_sel_hi:[1,0]
	v_pk_mul_f32 v[124:125], v[96:97], v[118:119] op_sel_hi:[1,0]
	v_pk_mul_f32 v[118:119], v[98:99], v[118:119] op_sel_hi:[1,0]
	v_pk_mul_f32 v[98:99], v[14:15], v[110:111]
	v_pk_mul_f32 v[96:97], v[12:13], v[108:109]
	v_pk_mul_f32 v[102:103], v[6:7], v[106:107]
	v_pk_mul_f32 v[100:101], v[4:5], v[104:105]
	v_pk_mul_f32 v[106:107], v[10:11], v[122:123]
	v_pk_mul_f32 v[104:105], v[8:9], v[120:121]
	v_pk_mul_f32 v[110:111], v[2:3], v[118:119]
	v_pk_mul_f32 v[108:109], v[0:1], v[124:125]
	global_store_dwordx4 v[114:115], v[96:99], off
	global_store_dwordx4 v[114:115], v[100:103], off offset:16
	global_store_dwordx4 v[114:115], v[104:107], off offset:512
	global_store_dwordx4 v[114:115], v[108:111], off offset:528
	global_load_dword v96, v[116:117], off sc1
	v_lshl_add_u64 v[98:99], v[138:139], 2, s[0:1]
	s_waitcnt vmcnt(0)
	v_fmamk_f32 v96, v96, 0x3a000000, v160
	v_mul_f32_e32 v97, 0x4b800000, v96
	v_cmp_gt_f32_e32 vcc, s2, v96
	s_nop 1
	v_cndmask_b32_e32 v96, v96, v97, vcc
	v_rsq_f32_e32 v100, v96
	v_lshl_add_u64 v[96:97], v[168:169], 2, s[50:51]
	v_lshl_add_u64 v[96:97], v[96:97], 0, v[130:131]
	v_mul_f32_e32 v101, 0x45800000, v100
	v_cndmask_b32_e32 v100, v100, v101, vcc
	v_pk_mul_f32 v[92:93], v[92:93], v[100:101] op_sel_hi:[1,0]
	v_pk_mul_f32 v[94:95], v[94:95], v[100:101] op_sel_hi:[1,0]
	v_pk_mul_f32 v[88:89], v[88:89], v[100:101] op_sel_hi:[1,0]
	v_pk_mul_f32 v[90:91], v[90:91], v[100:101] op_sel_hi:[1,0]
	v_pk_mul_f32 v[102:103], v[84:85], v[100:101] op_sel_hi:[1,0]
	v_pk_mul_f32 v[104:105], v[86:87], v[100:101] op_sel_hi:[1,0]
	v_pk_mul_f32 v[106:107], v[80:81], v[100:101] op_sel_hi:[1,0]
	v_pk_mul_f32 v[100:101], v[82:83], v[100:101] op_sel_hi:[1,0]
	v_pk_mul_f32 v[82:83], v[14:15], v[94:95]
	v_pk_mul_f32 v[80:81], v[12:13], v[92:93]
	v_pk_mul_f32 v[86:87], v[6:7], v[90:91]
	v_pk_mul_f32 v[84:85], v[4:5], v[88:89]
	v_pk_mul_f32 v[90:91], v[10:11], v[104:105]
	v_pk_mul_f32 v[88:89], v[8:9], v[102:103]
	v_pk_mul_f32 v[94:95], v[2:3], v[100:101]
	v_pk_mul_f32 v[92:93], v[0:1], v[106:107]
	global_store_dwordx4 v[96:97], v[80:83], off
	global_store_dwordx4 v[96:97], v[84:87], off offset:16
	global_store_dwordx4 v[96:97], v[88:91], off offset:512
	global_store_dwordx4 v[96:97], v[92:95], off offset:528
	global_load_dword v80, v[98:99], off sc1
	s_waitcnt vmcnt(0)
	v_fmamk_f32 v80, v80, 0x3a000000, v160
	v_mul_f32_e32 v81, 0x4b800000, v80
	v_cmp_gt_f32_e32 vcc, s2, v80
	s_nop 1
	v_cndmask_b32_e32 v80, v80, v81, vcc
	v_rsq_f32_e32 v82, v80
	v_lshl_add_u64 v[80:81], v[166:167], 2, s[50:51]
	v_lshl_add_u64 v[80:81], v[80:81], 0, v[130:131]
	v_mul_f32_e32 v83, 0x45800000, v82
	v_cndmask_b32_e32 v82, v82, v83, vcc
	v_pk_mul_f32 v[76:77], v[76:77], v[82:83] op_sel_hi:[1,0]
	v_pk_mul_f32 v[78:79], v[78:79], v[82:83] op_sel_hi:[1,0]
	v_pk_mul_f32 v[72:73], v[72:73], v[82:83] op_sel_hi:[1,0]
	v_pk_mul_f32 v[74:75], v[74:75], v[82:83] op_sel_hi:[1,0]
	v_pk_mul_f32 v[84:85], v[68:69], v[82:83] op_sel_hi:[1,0]
	v_pk_mul_f32 v[86:87], v[70:71], v[82:83] op_sel_hi:[1,0]
	v_pk_mul_f32 v[88:89], v[64:65], v[82:83] op_sel_hi:[1,0]
	v_pk_mul_f32 v[82:83], v[66:67], v[82:83] op_sel_hi:[1,0]
	v_pk_mul_f32 v[66:67], v[14:15], v[78:79]
	v_pk_mul_f32 v[64:65], v[12:13], v[76:77]
	v_pk_mul_f32 v[70:71], v[6:7], v[74:75]
	v_pk_mul_f32 v[68:69], v[4:5], v[72:73]
	v_pk_mul_f32 v[74:75], v[10:11], v[86:87]
	v_pk_mul_f32 v[72:73], v[8:9], v[84:85]
	v_pk_mul_f32 v[78:79], v[2:3], v[82:83]
	v_pk_mul_f32 v[76:77], v[0:1], v[88:89]
	global_store_dwordx4 v[80:81], v[64:67], off
	global_store_dwordx4 v[80:81], v[68:71], off offset:16
	global_store_dwordx4 v[80:81], v[72:75], off offset:512
	global_store_dwordx4 v[80:81], v[76:79], off offset:528
	global_load_dword v64, v[112:113], off offset:512 sc1
	s_waitcnt vmcnt(0)
	v_fmamk_f32 v64, v64, 0x3a000000, v160
	v_mul_f32_e32 v65, 0x4b800000, v64
	v_cmp_gt_f32_e32 vcc, s2, v64
	s_nop 1
	v_cndmask_b32_e32 v64, v64, v65, vcc
	v_rsq_f32_e32 v66, v64
	v_lshl_add_u64 v[64:65], v[164:165], 2, s[50:51]
	v_lshl_add_u64 v[64:65], v[64:65], 0, v[130:131]
	v_mul_f32_e32 v67, 0x45800000, v66
	v_cndmask_b32_e32 v66, v66, v67, vcc
	v_pk_mul_f32 v[60:61], v[60:61], v[66:67] op_sel_hi:[1,0]
	v_pk_mul_f32 v[62:63], v[62:63], v[66:67] op_sel_hi:[1,0]
	v_pk_mul_f32 v[56:57], v[56:57], v[66:67] op_sel_hi:[1,0]
	v_pk_mul_f32 v[58:59], v[58:59], v[66:67] op_sel_hi:[1,0]
	v_pk_mul_f32 v[68:69], v[52:53], v[66:67] op_sel_hi:[1,0]
	v_pk_mul_f32 v[70:71], v[54:55], v[66:67] op_sel_hi:[1,0]
	v_pk_mul_f32 v[72:73], v[48:49], v[66:67] op_sel_hi:[1,0]
	v_pk_mul_f32 v[66:67], v[50:51], v[66:67] op_sel_hi:[1,0]
	v_pk_mul_f32 v[50:51], v[14:15], v[62:63]
	v_pk_mul_f32 v[48:49], v[12:13], v[60:61]
	v_pk_mul_f32 v[54:55], v[6:7], v[58:59]
	v_pk_mul_f32 v[52:53], v[4:5], v[56:57]
	v_pk_mul_f32 v[58:59], v[10:11], v[70:71]
	v_pk_mul_f32 v[56:57], v[8:9], v[68:69]
	v_pk_mul_f32 v[62:63], v[2:3], v[66:67]
	v_pk_mul_f32 v[60:61], v[0:1], v[72:73]
	global_store_dwordx4 v[64:65], v[48:51], off
	global_store_dwordx4 v[64:65], v[52:55], off offset:16
	global_store_dwordx4 v[64:65], v[56:59], off offset:512
	global_store_dwordx4 v[64:65], v[60:63], off offset:528
	global_load_dword v48, v[112:113], off offset:576 sc1
	s_waitcnt vmcnt(0)
	v_fmamk_f32 v48, v48, 0x3a000000, v160
	v_mul_f32_e32 v49, 0x4b800000, v48
	v_cmp_gt_f32_e32 vcc, s2, v48
	s_nop 1
	v_cndmask_b32_e32 v48, v48, v49, vcc
	v_rsq_f32_e32 v50, v48
	v_lshl_add_u64 v[48:49], v[158:159], 2, s[50:51]
	v_lshl_add_u64 v[48:49], v[48:49], 0, v[130:131]
	v_mul_f32_e32 v51, 0x45800000, v50
	v_cndmask_b32_e32 v50, v50, v51, vcc
	v_pk_mul_f32 v[44:45], v[44:45], v[50:51] op_sel_hi:[1,0]
	v_pk_mul_f32 v[46:47], v[46:47], v[50:51] op_sel_hi:[1,0]
	v_pk_mul_f32 v[40:41], v[40:41], v[50:51] op_sel_hi:[1,0]
	v_pk_mul_f32 v[42:43], v[42:43], v[50:51] op_sel_hi:[1,0]
	v_pk_mul_f32 v[52:53], v[36:37], v[50:51] op_sel_hi:[1,0]
	v_pk_mul_f32 v[54:55], v[38:39], v[50:51] op_sel_hi:[1,0]
	v_pk_mul_f32 v[56:57], v[32:33], v[50:51] op_sel_hi:[1,0]
	v_pk_mul_f32 v[50:51], v[34:35], v[50:51] op_sel_hi:[1,0]
	v_pk_mul_f32 v[34:35], v[14:15], v[46:47]
	v_pk_mul_f32 v[32:33], v[12:13], v[44:45]
	v_pk_mul_f32 v[38:39], v[6:7], v[42:43]
	v_pk_mul_f32 v[36:37], v[4:5], v[40:41]
	v_pk_mul_f32 v[42:43], v[10:11], v[54:55]
	v_pk_mul_f32 v[40:41], v[8:9], v[52:53]
	v_pk_mul_f32 v[46:47], v[2:3], v[50:51]
	v_pk_mul_f32 v[44:45], v[0:1], v[56:57]
	global_store_dwordx4 v[48:49], v[32:35], off
	global_store_dwordx4 v[48:49], v[36:39], off offset:16
	global_store_dwordx4 v[48:49], v[40:43], off offset:512
	global_store_dwordx4 v[48:49], v[44:47], off offset:528
	global_load_dword v32, v[112:113], off offset:640 sc1
	s_waitcnt vmcnt(0)
	v_fmamk_f32 v32, v32, 0x3a000000, v160
	v_mul_f32_e32 v33, 0x4b800000, v32
	v_cmp_gt_f32_e32 vcc, s2, v32
	s_nop 1
	v_cndmask_b32_e32 v32, v32, v33, vcc
	v_rsq_f32_e32 v34, v32
	v_lshl_add_u64 v[32:33], v[156:157], 2, s[50:51]
	v_lshl_add_u64 v[32:33], v[32:33], 0, v[130:131]
	v_mul_f32_e32 v35, 0x45800000, v34
	v_cndmask_b32_e32 v34, v34, v35, vcc
	v_pk_mul_f32 v[28:29], v[28:29], v[34:35] op_sel_hi:[1,0]
	v_pk_mul_f32 v[30:31], v[30:31], v[34:35] op_sel_hi:[1,0]
	v_pk_mul_f32 v[24:25], v[24:25], v[34:35] op_sel_hi:[1,0]
	v_pk_mul_f32 v[26:27], v[26:27], v[34:35] op_sel_hi:[1,0]
	v_pk_mul_f32 v[36:37], v[20:21], v[34:35] op_sel_hi:[1,0]
	v_pk_mul_f32 v[38:39], v[22:23], v[34:35] op_sel_hi:[1,0]
	v_pk_mul_f32 v[40:41], v[16:17], v[34:35] op_sel_hi:[1,0]
	v_pk_mul_f32 v[34:35], v[18:19], v[34:35] op_sel_hi:[1,0]
	v_pk_mul_f32 v[18:19], v[14:15], v[30:31]
	v_pk_mul_f32 v[16:17], v[12:13], v[28:29]
	v_pk_mul_f32 v[22:23], v[6:7], v[26:27]
	v_pk_mul_f32 v[20:21], v[4:5], v[24:25]
	v_pk_mul_f32 v[26:27], v[10:11], v[38:39]
	v_pk_mul_f32 v[24:25], v[8:9], v[36:37]
	v_pk_mul_f32 v[30:31], v[2:3], v[34:35]
	v_pk_mul_f32 v[28:29], v[0:1], v[40:41]
	global_store_dwordx4 v[32:33], v[16:19], off
	global_store_dwordx4 v[32:33], v[20:23], off offset:16
	global_store_dwordx4 v[32:33], v[24:27], off offset:512
	global_store_dwordx4 v[32:33], v[28:31], off offset:528
	global_load_dword v16, v[112:113], off offset:704 sc1
	s_waitcnt vmcnt(0)
	v_fmac_f32_e32 v160, 0x3a000000, v16
	v_mul_f32_e32 v16, 0x4b800000, v160
	v_cmp_gt_f32_e32 vcc, s2, v160
	s_nop 1
	v_cndmask_b32_e32 v16, v160, v16, vcc
	v_rsq_f32_e32 v18, v16
	v_lshl_add_u64 v[16:17], v[134:135], 2, s[50:51]
	v_lshl_add_u64 v[16:17], v[16:17], 0, v[130:131]
	v_mul_f32_e32 v19, 0x45800000, v18
	v_cndmask_b32_e32 v18, v18, v19, vcc
	v_pk_mul_f32 v[20:21], v[154:155], v[18:19] op_sel_hi:[1,0]
	v_pk_mul_f32 v[22:23], v[152:153], v[18:19] op_sel_hi:[1,0]
	v_pk_mul_f32 v[24:25], v[150:151], v[18:19] op_sel_hi:[1,0]
	v_pk_mul_f32 v[26:27], v[148:149], v[18:19] op_sel_hi:[1,0]
	v_pk_mul_f32 v[28:29], v[146:147], v[18:19] op_sel_hi:[1,0]
	v_pk_mul_f32 v[30:31], v[144:145], v[18:19] op_sel_hi:[1,0]
	v_pk_mul_f32 v[32:33], v[142:143], v[18:19] op_sel_hi:[1,0]
	v_pk_mul_f32 v[18:19], v[140:141], v[18:19] op_sel_hi:[1,0]
	v_pk_mul_f32 v[14:15], v[14:15], v[22:23]
	v_pk_mul_f32 v[12:13], v[12:13], v[20:21]
	v_pk_mul_f32 v[6:7], v[6:7], v[26:27]
	v_pk_mul_f32 v[4:5], v[4:5], v[24:25]
	v_pk_mul_f32 v[10:11], v[10:11], v[30:31]
	v_pk_mul_f32 v[8:9], v[8:9], v[28:29]
	v_pk_mul_f32 v[2:3], v[2:3], v[18:19]
	v_pk_mul_f32 v[0:1], v[0:1], v[32:33]
	global_store_dwordx4 v[16:17], v[12:15], off
	global_store_dwordx4 v[16:17], v[4:7], off offset:16
	global_store_dwordx4 v[16:17], v[8:11], off offset:512
	global_store_dwordx4 v[16:17], v[0:3], off offset:528
	s_cmp_lg_u32 s2, 0
	s_cbranch_scc1 .Lflag_clr_done1
	v_readlane_b32 s4, v240, 9
	v_readlane_b32 s5, v240, 10
	v_readlane_b32 s6, v240, 35
	v_readlane_b32 s7, v240, 36
	s_and_b64 exec, exec, s[4:5]
	s_cbranch_execz .Lflag_clr_done1
	v_mov_b32_e32 v1, 0
	v_mov_b32_e32 v2, 0x3800
	s_nop 4
	global_store_dword v2, v1, s[6:7] sc0 sc1
.Lflag_clr_done1:
	s_endpgm
	.section	.rodata,"a",@progbits
	.p2align	6, 0x0
	.amdhsa_kernel _Z8fwd_mega4Args
		.amdhsa_group_segment_fixed_size 0
		.amdhsa_private_segment_fixed_size 0
		.amdhsa_kernarg_size 512
		.amdhsa_user_sgpr_count 2
		.amdhsa_user_sgpr_dispatch_ptr 0
		.amdhsa_user_sgpr_queue_ptr 0
		.amdhsa_user_sgpr_kernarg_segment_ptr 1
		.amdhsa_user_sgpr_dispatch_id 0
		.amdhsa_user_sgpr_kernarg_preload_length 0
		.amdhsa_user_sgpr_kernarg_preload_offset 0
		.amdhsa_user_sgpr_private_segment_size 0
		.amdhsa_uses_dynamic_stack 0
		.amdhsa_enable_private_segment 0
		.amdhsa_system_sgpr_workgroup_id_x 1
		.amdhsa_system_sgpr_workgroup_id_y 0
		.amdhsa_system_sgpr_workgroup_id_z 0
		.amdhsa_system_sgpr_workgroup_info 0
		.amdhsa_system_vgpr_workitem_id 2
		.amdhsa_next_free_vgpr 247
		.amdhsa_next_free_sgpr 100
		.amdhsa_accum_offset 248
		.amdhsa_reserve_vcc 1
		.amdhsa_float_round_mode_32 0
		.amdhsa_float_round_mode_16_64 0
		.amdhsa_float_denorm_mode_32 3
		.amdhsa_float_denorm_mode_16_64 3
		.amdhsa_dx10_clamp 1
		.amdhsa_ieee_mode 1
		.amdhsa_fp16_overflow 0
		.amdhsa_tg_split 0
		.amdhsa_exception_fp_ieee_invalid_op 0
		.amdhsa_exception_fp_denorm_src 0
		.amdhsa_exception_fp_ieee_div_zero 0
		.amdhsa_exception_fp_ieee_overflow 0
		.amdhsa_exception_fp_ieee_underflow 0
		.amdhsa_exception_fp_ieee_inexact 0
		.amdhsa_exception_int_div_zero 0
	.end_amdhsa_kernel

amdhsa.kernels:
  - .agpr_count:     0
    .args:
      - .offset:         0
        .size:           256
        .value_kind:     by_value
      - .offset:         256
        .size:           4
        .value_kind:     hidden_block_count_x
      - .offset:         260
        .size:           4
        .value_kind:     hidden_block_count_y
      - .offset:         264
        .size:           4
        .value_kind:     hidden_block_count_z
      - .offset:         268
        .size:           2
        .value_kind:     hidden_group_size_x
      - .offset:         270
        .size:           2
        .value_kind:     hidden_group_size_y
      - .offset:         272
        .size:           2
        .value_kind:     hidden_group_size_z
      - .offset:         274
        .size:           2
        .value_kind:     hidden_remainder_x
      - .offset:         276
        .size:           2
        .value_kind:     hidden_remainder_y
      - .offset:         278
        .size:           2
        .value_kind:     hidden_remainder_z
      - .offset:         296
        .size:           8
        .value_kind:     hidden_global_offset_x
      - .offset:         304
        .size:           8
        .value_kind:     hidden_global_offset_y
      - .offset:         312
        .size:           8
        .value_kind:     hidden_global_offset_z
      - .offset:         320
        .size:           2
        .value_kind:     hidden_grid_dims
      - .offset:         344
        .size:           8
        .value_kind:     hidden_multigrid_sync_arg
      - .offset:         376
        .size:           4
        .value_kind:     hidden_dynamic_lds_size
    .group_segment_fixed_size: 0
    .kernarg_segment_align: 8
    .kernarg_segment_size: 512
    .language:       OpenCL C
    .language_version:
      - 2
      - 0
    .max_flat_workgroup_size: 512
    .name:           _Z8fwd_mega4Args
    .private_segment_fixed_size: 0
    .sgpr_count:     106
    .sgpr_spill_count: 37
    .symbol:         _Z8fwd_mega4Args.kd
    .uniform_work_group_size: 1
    .uses_dynamic_stack: false
    .vgpr_count:     247
    .vgpr_spill_count: 0
    .wavefront_size: 64
